# static s_setprio 1 for waves 4-7 during the attention phase (strategy: one static priority raise for the younger half), on top of v26
# speedup vs baseline: 1.0064x; 1.0064x over previous
.LBB0_293:
	s_cmp_lt_i32 s28, 4
	s_cselect_b64 s[0:1], -1, 0
	s_cmp_gt_i32 s29, 3
	s_cselect_b64 s[2:3], -1, 0
	s_and_b64 s[0:1], s[0:1], s[2:3]
	s_andn2_b64 vcc, exec, s[0:1]
	s_cbranch_vccnz .LBB0_659
	s_cmp_lt_u32 s79, 4
	s_cbranch_scc1 .Lattn_prio_skip
	s_setprio 1
.Lattn_prio_skip:
	s_add_u32 s66, s74, 0x1c600000
	s_addc_u32 s67, s75, 0
	s_add_u32 s76, s74, 0x1e600000
	s_addc_u32 s77, s75, 0
	s_add_u32 s80, s74, 0x20600000
	s_addc_u32 s81, s75, 0
	s_add_u32 s82, s74, 0x26600000
	s_addc_u32 s83, s75, 0
	s_add_u32 s84, s74, 0x2a600000
	s_addc_u32 s85, s75, 0
	s_add_u32 s6, s74, 0x180000
	s_addc_u32 s7, s75, 0
	s_ashr_i32 s0, s14, 3
	s_mul_hi_i32 s1, s0, 0x66666667
	s_lshr_b32 s2, s1, 31
	s_ashr_i32 s1, s1, 1
	v_writelane_b32 v255, s94, 20
	s_add_i32 s1, s1, s2
	s_mul_i32 s1, s1, 5
	v_writelane_b32 v255, s95, 21
	v_writelane_b32 v255, s88, 18
	s_sub_i32 s86, s0, s1
	s_cmpk_lt_i32 s78, 0x100
	v_writelane_b32 v255, s89, 19
	v_writelane_b32 v255, s97, 22
	s_cselect_b64 s[0:1], -1, 0
	v_writelane_b32 v255, s0, 23
	s_cmpk_gt_i32 s78, 0xff
	s_nop 0
	v_writelane_b32 v255, s1, 24
	s_cbranch_scc1 .LBB0_402
	s_cmp_gt_i32 s86, 0
	s_cselect_b64 s[0:1], -1, 0
	s_add_u32 s16, s74, 0x180010
	v_cndmask_b32_e64 v1, 0, 1, s[0:1]
	s_waitcnt vmcnt(0) lgkmcnt(0)
	v_mbcnt_lo_u32_b32 v2, -1, 0
	s_mov_b32 s11, 0
	s_addc_u32 s17, s75, 0
	v_cmp_ne_u32_e64 s[2:3], 1, v1
	v_mov_b32_e32 v3, 0
	s_mov_b64 s[18:19], 0x80
	s_mov_b64 s[20:21], 0x40000
	s_mov_b64 s[22:23], 0x80000
	s_mov_b64 s[24:25], 0xc0000
	s_mov_b64 s[26:27], 0x100000
	s_mov_b32 s87, 0x41000000
	v_mov_b32_e32 v1, 0x358637bd
	s_mov_b32 s88, 0xf800000
	v_mov_b32_e32 v223, 0x260
	s_mov_b32 s89, 0x3f4ccccd
	v_mov_b32_e32 v230, 0xff800000
	v_mbcnt_hi_u32_b32 v231, -1, v2
	s_mov_b32 s90, s78
	s_branch .LBB0_297

.LBB0_601:
	s_setprio 0
	s_cmp_lt_i32 s29, 5
	s_cbranch_scc1 .LBB0_659
	s_waitcnt vmcnt(0)
	s_waitcnt lgkmcnt(0)
	s_barrier
	s_and_saveexec_b64 s[0:1], s[88:89]
	s_cbranch_execz .LBB0_658
	s_add_i32 s2, 0, 0x20160
	v_mov_b32_e32 v1, s2
	s_waitcnt vmcnt(0) expcnt(0) lgkmcnt(0)
	ds_read_b32 v3, v1
	s_add_i32 s2, 0, 0x20164
	v_mov_b32_e32 v1, s2
	ds_read_b32 v1, v1
	s_waitcnt lgkmcnt(1)
	v_cmp_ne_u32_e32 vcc, 0, v3
	s_cbranch_vccnz .LBB0_618
	v_readlane_b32 s2, v255, 0
	v_readlane_b32 s3, v255, 1
	s_load_dwordx2 s[6:7], s[2:3], 0x4
	s_add_u32 s2, s74, 0x4200
	s_addc_u32 s3, s75, 0
	s_add_u32 s4, s74, 0x4400
	s_addc_u32 s5, s75, 0
	s_waitcnt lgkmcnt(0)
	s_mul_i32 s12, s6, s33
	s_add_u32 s6, s74, 0x4500
	s_mul_i32 s12, s12, s7
	s_addc_u32 s7, s75, 0
	s_add_u32 s8, s74, 0x4600
	s_addc_u32 s9, s75, 0
	s_add_u32 s10, s74, 0x4700
	s_addc_u32 s11, s75, 0
	s_add_u32 s16, s74, 0x4800
	s_addc_u32 s17, s75, 0
	s_add_u32 s18, s74, 0x4900
	s_addc_u32 s19, s75, 0
	s_add_u32 s20, s74, 0x4a00
	s_addc_u32 s21, s75, 0
	s_add_u32 s22, s74, 0x4b00
	s_addc_u32 s23, s75, 0
	s_add_u32 s24, s74, 0x4c00
	s_addc_u32 s25, s75, 0
	s_add_u32 s26, s74, 0x4d00
	s_addc_u32 s27, s75, 0
	s_add_u32 s38, s74, 0x4e00
	s_addc_u32 s39, s75, 0
	s_add_u32 s40, s74, 0x4f00
	s_addc_u32 s41, s75, 0
	s_add_u32 s42, s74, 0x5000
	s_addc_u32 s43, s75, 0
	s_add_u32 s44, s74, 0x5100
	s_addc_u32 s45, s75, 0
	s_add_u32 s48, s74, 0x5200
	s_addc_u32 s49, s75, 0
	s_add_u32 s50, s74, 0x5300
	s_addc_u32 s51, s75, 0
	s_mov_b32 s13, 1
	v_mov_b32_e32 v17, 0
	s_branch .LBB0_606
